# mLSTM units: wave-0 64-lane prefix sum / prefix max by DPP row ops (row_shr + row_bcast) and v_readlane instead of 12-14 ds_bpermute round trips
# speedup vs baseline: 1.0062x; 1.0062x over previous
; __device__ __forceinline__ void mlstm_out_unit(const Params& p, int layer, int uci, char* smem) {
;     ...
;     if (wid == 0) {
;         float x = F[lane];
; #pragma unroll
;         for (int o = 1; o < 64; o <<= 1) { const float y = __shfl_up(x, o); if (lane >= o) x += y; }
;         const float aj = F[64 + lane] - x;
;         float pm = aj;
; #pragma unroll
;         for (int o = 1; o < 64; o <<= 1) { const float y = __shfl_up(pm, o); if (lane >= o) pm = fmaxf(pm, y); }
;         const float mx = fmaxf(mst, pm);
;         F[128 + lane] = expf(aj);
;         F[192 + lane] = expf(-mx);
;         F[256 + lane] = expf(mst - mx);
;         F[320 + lane] = expf(-(x + mx));
;     }
.LBB0_524:
	s_or_b64 exec, exec, s[0:1]
	v_cmp_lt_u32_e32 vcc, 63, v28
	s_waitcnt lgkmcnt(0)
	s_barrier
	s_and_saveexec_b64 s[0:1], vcc
	s_xor_b64 s[0:1], exec, s[0:1]
	v_mbcnt_hi_u32_b32 v18, -1, v194
	v_and_b32_e32 v16, 64, v18
	s_or_saveexec_b64 s[54:55], s[0:1]
	v_and_b32_e32 v17, 63, v28
	s_xor_b64 exec, exec, s[54:55]
	s_cbranch_execz .LBB0_469
	v_lshlrev_b32_e32 v0, 2, v17
	ds_read_b32 v0, v0 offset:25856
	ds_read_b32 v8, v2 offset:26112
	s_mov_b32 s4, 0xc2ce8ed0
	s_mov_b32 s5, 0x42b17218
	s_mov_b32 s6, 0x42ce8ed0
	s_mov_b32 s7, 0xc2b17218
	s_mov_b32 s37, 0x3fb8aa3b
	s_mov_b32 s38, 0xc2ce8ed0
	s_mov_b32 s39, 0x42b17218
	s_mov_b32 s1, 0x3fb8aa3b
	s_mov_b32 s0, 0xbfb8aa3b
	v_and_b32_e32 v16, 64, v195
	v_mov_b32_e32 v18, v195
	s_waitcnt lgkmcnt(0)
	s_nop 1
	v_add_f32_dpp v0, v0, v0 row_shr:1 row_mask:0xf bank_mask:0xf
	s_nop 1
	v_add_f32_dpp v0, v0, v0 row_shr:2 row_mask:0xf bank_mask:0xf
	s_nop 1
	v_add_f32_dpp v0, v0, v0 row_shr:4 row_mask:0xf bank_mask:0xf
	s_nop 1
	v_add_f32_dpp v0, v0, v0 row_shr:8 row_mask:0xf bank_mask:0xf
	s_nop 1
	v_add_f32_dpp v0, v0, v0 row_bcast:15 row_mask:0xa bank_mask:0xf
	s_nop 1
	v_add_f32_dpp v0, v0, v0 row_bcast:31 row_mask:0xc bank_mask:0xf
	v_sub_f32_e32 v8, v8, v0
	v_mov_b32_e32 v1, v8
	s_nop 1
	v_max_f32_dpp v1, v1, v1 row_shr:1 row_mask:0xf bank_mask:0xf
	s_nop 1
	v_max_f32_dpp v1, v1, v1 row_shr:2 row_mask:0xf bank_mask:0xf
	s_nop 1
	v_max_f32_dpp v1, v1, v1 row_shr:4 row_mask:0xf bank_mask:0xf
	s_nop 1
	v_max_f32_dpp v1, v1, v1 row_shr:8 row_mask:0xf bank_mask:0xf
	s_nop 1
	v_max_f32_dpp v1, v1, v1 row_bcast:15 row_mask:0xa bank_mask:0xf
	s_nop 1
	v_max_f32_dpp v1, v1, v1 row_bcast:31 row_mask:0xc bank_mask:0xf
	v_cmp_ngt_f32_e32 vcc, s4, v8
	v_max_f32_e32 v1, v1, v1
	v_max_f32_e32 v3, v40, v40
	v_max_f32_e32 v1, v3, v1
	v_mul_f32_e32 v3, 0x3fb8aa3b, v8
	v_fma_f32 v4, v8, s1, -v3
	v_rndne_f32_e32 v5, v3
	v_fmac_f32_e32 v4, 0x32a5705f, v8
	v_sub_f32_e32 v3, v3, v5
	v_add_f32_e32 v3, v3, v4
	v_exp_f32_e32 v3, v3
	v_cvt_i32_f32_e32 v4, v5
	v_add_f32_e32 v0, v0, v1
	v_ldexp_f32 v3, v3, v4
	v_mul_f32_e32 v4, 0xbfb8aa3b, v1
	v_fma_f32 v5, v1, s0, -v4
	v_rndne_f32_e32 v6, v4
	v_fmac_f32_e32 v5, 0xb2a5705f, v1
	v_sub_f32_e32 v4, v4, v6
	v_add_f32_e32 v4, v4, v5
	v_exp_f32_e32 v4, v4
	v_cvt_i32_f32_e32 v5, v6
	v_cndmask_b32_e32 v3, 0, v3, vcc
	v_cmp_nlt_f32_e32 vcc, s5, v8
	v_ldexp_f32 v4, v4, v5
	s_nop 0
	v_cndmask_b32_e32 v3, v202, v3, vcc
	v_cmp_nlt_f32_e32 vcc, s6, v1
	s_nop 1
	v_cndmask_b32_e32 v4, 0, v4, vcc
	v_cmp_ngt_f32_e32 vcc, s7, v1
	s_nop 1
	v_cndmask_b32_e32 v4, v202, v4, vcc
	ds_write2st64_b32 v2, v3, v4 offset0:103 offset1:104
	v_sub_f32_e32 v3, v40, v1
	v_mul_f32_e32 v4, 0x3fb8aa3b, v3
	v_fma_f32 v5, v3, s1, -v4
	v_rndne_f32_e32 v6, v4
	v_fmac_f32_e32 v5, 0x32a5705f, v3
	v_sub_f32_e32 v4, v4, v6
	v_add_f32_e32 v4, v4, v5
	v_exp_f32_e32 v4, v4
	v_cvt_i32_f32_e32 v5, v6
	v_cmp_ngt_f32_e32 vcc, s4, v3
	v_mul_f32_e32 v1, 0xbfb8aa3b, v0
	v_ldexp_f32 v4, v4, v5
	v_cndmask_b32_e32 v4, 0, v4, vcc
	v_cmp_nlt_f32_e32 vcc, s5, v3
	v_rndne_f32_e32 v5, v1
	s_nop 0
	v_cndmask_b32_e32 v3, v202, v4, vcc
	v_fma_f32 v4, v0, s0, -v1
	v_fmac_f32_e32 v4, 0xb2a5705f, v0
	v_sub_f32_e32 v1, v1, v5
	v_add_f32_e32 v1, v1, v4
	v_exp_f32_e32 v1, v1
	v_cvt_i32_f32_e32 v4, v5
	v_cmp_nlt_f32_e32 vcc, s6, v0
	v_ldexp_f32 v1, v1, v4
	s_nop 0
	v_cndmask_b32_e32 v1, 0, v1, vcc
	v_cmp_ngt_f32_e32 vcc, s7, v0
	s_nop 1
	v_cndmask_b32_e32 v0, v202, v1, vcc
	ds_write2st64_b32 v2, v3, v0 offset0:105 offset1:106
	s_branch .LBB0_469

; __device__ __forceinline__ void mlstm_local_unit(const Params& p, int layer, int uci, char* smem) {
;     ...
;         const bf16x8 v0 = *(const bf16x8*)(zr + 256 + h * 64 + part * 16), v1 = *(const bf16x8*)(zr + 256 + h * 64 + part * 16 + 8);
; #pragma unroll
;         for (int j = 0; j < 8; ++j) { *(bf16_t*)(smem + LV + (part * 16 + j) * 144 + s * 2) = (bf16_t)v0[j]; *(bf16_t*)(smem + LV + (part * 16 + 8 + j) * 144 + s * 2) = (bf16_t)v1[j]; }
;     }
;     __syncthreads();
;     if (wid == 0) {
;         float x = F[lane];
; #pragma unroll
;         for (int o = 1; o < 64; o <<= 1) { const float y = __shfl_up(x, o); if (lane >= o) x += y; }
;         float pm = F[64 + lane] - x;
;         const float aj = pm;
; #pragma unroll
;         for (int o = 1; o < 64; o <<= 1) { const float y = __shfl_up(pm, o); if (lane >= o) pm = fmaxf(pm, y); }
;         const float g = __shfl(x, 63), pm63 = __shfl(pm, 63);
;         F[128 + lane] = expf(aj - pm63);
;         if (lane == 0) { F[192] = g; F[193] = pm63; }
;     }
.LBB0_593:
	s_or_b64 exec, exec, s[0:1]
	s_lshl_b32 s0, s44, 5
	v_lshl_or_b32 v16, v45, 3, s0
	v_lshlrev_b32_e32 v104, 1, v16
	v_lshl_add_u64 v[14:15], v[12:13], 0, v[104:105]
	global_load_dwordx4 v[0:3], v[14:15], off offset:256
	s_movk_i32 s0, 0x100
	v_cmp_gt_i32_e64 s[0:1], s0, v8
	s_nop 1
	v_cndmask_b32_e64 v4, v205, 0, s[0:1]
	v_cmp_gt_i32_e32 vcc, v8, v4
	global_load_dwordx4 v[4:7], v[14:15], off offset:-1312
	v_cndmask_b32_e64 v9, v204, v205, s[0:1]
	v_add_u32_e32 v8, 1, v8
	v_cmp_lt_i32_e64 s[42:43], v8, v9
	global_load_dwordx4 v[8:11], v[14:15], off offset:1824
	s_lshl_b32 s0, s44, 7
	s_mov_b32 s1, s89
	v_lshl_add_u64 v[12:13], v[12:13], 0, s[0:1]
	v_lshlrev_b32_e32 v104, 5, v45
	v_readlane_b32 s0, v254, 44
	v_lshl_add_u64 v[12:13], v[12:13], 0, v[104:105]
	v_lshlrev_b32_e32 v40, 2, v16
	v_readlane_b32 s1, v254, 45
	global_load_dwordx4 v[50:53], v[12:13], off offset:512
	global_load_dwordx4 v[54:57], v[12:13], off offset:528
	s_nop 2
	global_load_dwordx4 v[12:15], v40, s[0:1] offset:528
	global_load_dwordx4 v[28:31], v40, s[0:1] offset:512
	global_load_dwordx4 v[20:23], v40, s[0:1] offset:1552
	global_load_dwordx4 v[36:39], v40, s[0:1] offset:1536
	global_load_dwordx4 v[16:19], v40, s[0:1] offset:2576
	global_load_dwordx4 v[32:35], v40, s[0:1] offset:2560
	v_readlane_b32 s0, v254, 46
	v_readlane_b32 s1, v254, 47
	s_nop 4
	global_load_dwordx4 v[24:27], v40, s[0:1] offset:528
	s_nop 0
	global_load_dwordx4 v[40:43], v40, s[0:1] offset:512
	v_lshlrev_b32_e32 v49, 1, v48
	v_mad_u32_u24 v46, v45, s33, v49
	v_cmp_gt_u32_e64 s[0:1], 64, v44
	s_waitcnt vmcnt(9)
	ds_write_b16 v46, v50 offset:4608
	s_waitcnt vmcnt(8)
	ds_write_b16 v46, v54 offset:5760
	ds_write_b16_d16_hi v46, v50 offset:4752
	ds_write_b16_d16_hi v46, v54 offset:5904
	ds_write_b16 v46, v51 offset:4896
	ds_write_b16 v46, v55 offset:6048
	ds_write_b16_d16_hi v46, v51 offset:5040
	ds_write_b16_d16_hi v46, v55 offset:6192
	ds_write_b16 v46, v52 offset:5184
	ds_write_b16 v46, v56 offset:6336
	ds_write_b16_d16_hi v46, v52 offset:5328
	ds_write_b16_d16_hi v46, v56 offset:6480
	ds_write_b16 v46, v53 offset:5472
	ds_write_b16 v46, v57 offset:6624
	ds_write_b16_d16_hi v46, v53 offset:5616
	ds_write_b16_d16_hi v46, v57 offset:6768
	s_waitcnt lgkmcnt(0)
	s_barrier
	s_and_saveexec_b64 s[34:35], s[0:1]
	s_cbranch_execz .LBB0_600
	v_and_b32_e32 v46, 63, v44
	v_lshlrev_b32_e32 v47, 2, v46
	ds_read_b32 v47, v47 offset:13824
	v_lshlrev_b32_e32 v56, 2, v44
	ds_read_b32 v57, v56 offset:14080
	v_cmp_eq_u32_e64 s[44:45], 0, v46
	s_waitcnt lgkmcnt(0)
	s_nop 1
	v_add_f32_dpp v47, v47, v47 row_shr:1 row_mask:0xf bank_mask:0xf
	s_nop 1
	v_add_f32_dpp v47, v47, v47 row_shr:2 row_mask:0xf bank_mask:0xf
	s_nop 1
	v_add_f32_dpp v47, v47, v47 row_shr:4 row_mask:0xf bank_mask:0xf
	s_nop 1
	v_add_f32_dpp v47, v47, v47 row_shr:8 row_mask:0xf bank_mask:0xf
	s_nop 1
	v_add_f32_dpp v47, v47, v47 row_bcast:15 row_mask:0xa bank_mask:0xf
	s_nop 1
	v_add_f32_dpp v47, v47, v47 row_bcast:31 row_mask:0xc bank_mask:0xf
	v_sub_f32_e32 v57, v57, v47
	v_mov_b32_e32 v50, v57
	s_nop 1
	v_max_f32_dpp v50, v50, v50 row_shr:1 row_mask:0xf bank_mask:0xf
	s_nop 1
	v_max_f32_dpp v50, v50, v50 row_shr:2 row_mask:0xf bank_mask:0xf
	s_nop 1
	v_max_f32_dpp v50, v50, v50 row_shr:4 row_mask:0xf bank_mask:0xf
	s_nop 1
	v_max_f32_dpp v50, v50, v50 row_shr:8 row_mask:0xf bank_mask:0xf
	s_nop 1
	v_max_f32_dpp v50, v50, v50 row_bcast:15 row_mask:0xa bank_mask:0xf
	s_nop 1
	v_max_f32_dpp v50, v50, v50 row_bcast:31 row_mask:0xc bank_mask:0xf
	s_nop 1
	v_readlane_b32 s0, v47, 63
	v_readlane_b32 s1, v50, 63
	s_nop 3
	v_mov_b32_e32 v46, s0
	v_mov_b32_e32 v47, s1
	v_sub_f32_e32 v50, v57, v47
	v_mul_f32_e32 v51, 0x3fb8aa3b, v50
	v_fma_f32 v52, v50, s37, -v51
	v_rndne_f32_e32 v53, v51
	v_fmac_f32_e32 v52, 0x32a5705f, v50
	v_sub_f32_e32 v51, v51, v53
	v_add_f32_e32 v51, v51, v52
	v_exp_f32_e32 v51, v51
	v_cvt_i32_f32_e32 v52, v53
	v_cmp_ngt_f32_e64 s[0:1], s38, v50
	v_ldexp_f32 v51, v51, v52
	s_nop 0
	v_cndmask_b32_e64 v51, 0, v51, s[0:1]
	v_cmp_nlt_f32_e64 s[0:1], s39, v50
	s_nop 1
	v_cndmask_b32_e64 v50, v202, v51, s[0:1]
	ds_write_b32 v56, v50 offset:14336
	s_and_b64 exec, exec, s[44:45]
	s_cbranch_execz .LBB0_600
	ds_write_b64 v105, v[46:47] offset:14592
